# attention step: row max across lane halves by v_permlane32_swap (no LDS round trip); first 8 V-fragment reads hoisted behind the QK MFMAs
# speedup vs baseline: 1.0113x; 1.0113x over previous
.LBB0_280:
	s_cmp_gt_u32 s49, s70
	s_cbranch_scc1 .LBB0_294
	s_add_i32 s51, s50, 0
	s_mul_i32 s52, s67, 0x2400
	s_add_i32 s52, s51, s52
	v_add3_u32 v68, s52, v172, v179
	ds_read_b128 v[64:67], v68
	ds_read_b128 v[132:135], v68 offset:32
	ds_read_b128 v[186:189], v68 offset:4608
	ds_read_b128 v[190:193], v68 offset:4640
	ds_read_b128 v[194:197], v68 offset:64
	ds_read_b128 v[198:201], v68 offset:96
	ds_read_b128 v[202:205], v68 offset:4672
	ds_read_b128 v[206:209], v68 offset:4704
	v_add_u32_e32 v130, s49, v182
	v_cvt_f32_u32_e32 v68, v130
	v_mov_b32_e32 v139, v138
	v_sub_f32_e32 v68, v68, v181
	v_fma_f32 v136, v138, v68, -v184
	v_fma_f32 v80, 0, v138, v136
	v_add_f32_e32 v81, v138, v136
	v_fma_f32 v82, v140, s36, v136
	v_fma_f32 v83, v141, s37, v136
	v_fma_f32 v84, v140, s14, v136
	v_fma_f32 v85, v141, s15, v136
	v_fma_f32 v86, v140, s24, v136
	v_fma_f32 v87, v141, s25, v136
	v_fma_f32 v88, v140, s30, v136
	v_fma_f32 v89, v141, s31, v136
	v_fma_f32 v90, v140, s88, v136
	v_fma_f32 v91, v141, s89, v136
	v_fma_f32 v92, v140, s96, v136
	v_fma_f32 v93, v141, s97, v136
	v_fma_f32 v94, v140, s6, v136
	v_fma_f32 v95, v141, s7, v136
	v_fma_f32 v78, v138, s18, v136
	v_fma_f32 v79, v139, s19, v136
	v_fma_f32 v76, v138, s22, v136
	v_fma_f32 v77, v139, s23, v136
	s_waitcnt lgkmcnt(7)
	v_mfma_f32_32x32x16_bf16 v[80:95], v[64:67], v[98:101], v[80:95]
	v_fma_f32 v74, v138, s44, v136
	v_fma_f32 v75, v139, s45, v136
	v_fma_f32 v72, v138, s26, v136
	v_fma_f32 v73, v139, s27, v136
	v_fma_f32 v70, v138, s28, v136
	v_fma_f32 v71, v139, s29, v136
	v_fma_f32 v68, v138, s4, v136
	v_fma_f32 v69, v139, s5, v136
	v_fma_f32 v66, v138, s10, v136
	v_fma_f32 v67, v139, s11, v136
	v_fma_f32 v64, v142, s84, v136
	v_fma_f32 v65, v143, s85, v136
	s_waitcnt lgkmcnt(6)
	v_mfma_f32_32x32x16_bf16 v[80:95], v[132:135], v[102:105], v[80:95]
	s_waitcnt lgkmcnt(5)
	v_mfma_f32_32x32x16_bf16 v[64:79], v[186:189], v[98:101], v[64:79]
	s_waitcnt lgkmcnt(4)
	v_mfma_f32_32x32x16_bf16 v[64:79], v[190:193], v[102:105], v[64:79]
	s_waitcnt lgkmcnt(3)
	v_mfma_f32_32x32x16_bf16 v[80:95], v[194:197], v[106:109], v[80:95]
	s_waitcnt lgkmcnt(1)
	v_mfma_f32_32x32x16_bf16 v[64:79], v[202:205], v[106:109], v[64:79]
	v_mfma_f32_32x32x16_bf16 v[80:95], v[198:201], v[110:113], v[80:95]
	s_waitcnt lgkmcnt(0)
	v_mfma_f32_32x32x16_bf16 v[64:79], v[206:209], v[110:113], v[64:79]
	v_add3_u32 v139, s51, v172, v180
	ds_read_b128 v[186:189], v139 offset:18432
	ds_read_b128 v[190:193], v139 offset:18464
	ds_read_b128 v[194:197], v139 offset:23040
	ds_read_b128 v[198:201], v139 offset:23072
	ds_read_b128 v[202:205], v139 offset:27648
	ds_read_b128 v[134:137], v139 offset:27680
	ds_read_b128 v[206:209], v139 offset:32256
	ds_read_b128 v[210:213], v139 offset:32288
	s_nop 2
	s_add_i32 s52, s49, 63
	s_cmp_le_u32 s52, s99
	s_cbranch_scc1 .LBB0_283
	v_add_u32_e32 v131, 32, v130
	v_cmp_le_u32_e32 vcc, v131, v183
	v_add_u32_e32 v131, 33, v130
	s_nop 5
	v_cndmask_b32_e32 v64, v158, v64, vcc
	v_cmp_lt_u32_e32 vcc, v130, v183
	s_nop 1
	v_cndmask_b32_e32 v81, v158, v81, vcc
	v_cmp_le_u32_e32 vcc, v130, v183
	s_nop 1
	v_cndmask_b32_e32 v80, v158, v80, vcc
	v_cmp_le_u32_e32 vcc, v131, v183
	v_add_u32_e32 v131, 2, v130
	s_nop 0
	v_cndmask_b32_e32 v65, v158, v65, vcc
	v_cmp_le_u32_e32 vcc, v131, v183
	v_add_u32_e32 v131, 34, v130
	s_nop 0
	v_cndmask_b32_e32 v82, v158, v82, vcc
	v_cmp_le_u32_e32 vcc, v131, v183
	v_add_u32_e32 v131, 3, v130
	s_nop 0
	v_cndmask_b32_e32 v66, v158, v66, vcc
	v_cmp_le_u32_e32 vcc, v131, v183
	v_add_u32_e32 v131, 35, v130
	s_nop 0
	v_cndmask_b32_e32 v83, v158, v83, vcc
	v_cmp_le_u32_e32 vcc, v131, v183
	v_add_u32_e32 v131, 4, v130
	s_nop 0
	v_cndmask_b32_e32 v67, v158, v67, vcc
	v_cmp_le_u32_e32 vcc, v131, v183
	v_add_u32_e32 v131, 36, v130
	s_nop 0
	v_cndmask_b32_e32 v84, v158, v84, vcc
	v_cmp_le_u32_e32 vcc, v131, v183
	v_add_u32_e32 v131, 5, v130
	s_nop 0
	v_cndmask_b32_e32 v68, v158, v68, vcc
	v_cmp_le_u32_e32 vcc, v131, v183
	v_add_u32_e32 v131, 37, v130
	s_nop 0
	v_cndmask_b32_e32 v85, v158, v85, vcc
	v_cmp_le_u32_e32 vcc, v131, v183
	v_add_u32_e32 v131, 6, v130
	s_nop 0
	v_cndmask_b32_e32 v69, v158, v69, vcc
	v_cmp_le_u32_e32 vcc, v131, v183
	v_add_u32_e32 v131, 38, v130
	s_nop 0
	v_cndmask_b32_e32 v86, v158, v86, vcc
	v_cmp_le_u32_e32 vcc, v131, v183
	v_add_u32_e32 v131, 7, v130
	s_nop 0
	v_cndmask_b32_e32 v70, v158, v70, vcc
	v_cmp_le_u32_e32 vcc, v131, v183
	v_add_u32_e32 v131, 39, v130
	s_nop 0
	v_cndmask_b32_e32 v87, v158, v87, vcc
	v_cmp_le_u32_e32 vcc, v131, v183
	v_add_u32_e32 v131, 16, v130
	s_nop 0
	v_cndmask_b32_e32 v71, v158, v71, vcc
	v_cmp_le_u32_e32 vcc, v131, v183
	v_add_u32_e32 v131, 48, v130
	s_nop 0
	v_cndmask_b32_e32 v88, v158, v88, vcc
	v_cmp_le_u32_e32 vcc, v131, v183
	v_add_u32_e32 v131, 17, v130
	s_nop 0
	v_cndmask_b32_e32 v72, v158, v72, vcc
	v_cmp_le_u32_e32 vcc, v131, v183
	v_add_u32_e32 v131, 49, v130
	s_nop 0
	v_cndmask_b32_e32 v89, v158, v89, vcc
	v_cmp_le_u32_e32 vcc, v131, v183
	v_add_u32_e32 v131, 18, v130
	s_nop 0
	v_cndmask_b32_e32 v73, v158, v73, vcc
	v_cmp_le_u32_e32 vcc, v131, v183
	v_add_u32_e32 v131, 50, v130
	s_nop 0
	v_cndmask_b32_e32 v90, v158, v90, vcc
	v_cmp_le_u32_e32 vcc, v131, v183
	v_add_u32_e32 v131, 19, v130
	s_nop 0
	v_cndmask_b32_e32 v74, v158, v74, vcc
	v_cmp_le_u32_e32 vcc, v131, v183
	v_add_u32_e32 v131, 51, v130
	s_nop 0
	v_cndmask_b32_e32 v91, v158, v91, vcc
	v_cmp_le_u32_e32 vcc, v131, v183
	v_add_u32_e32 v131, 20, v130
	s_nop 0
	v_cndmask_b32_e32 v75, v158, v75, vcc
	v_cmp_le_u32_e32 vcc, v131, v183
	v_add_u32_e32 v131, 52, v130
	s_nop 0
	v_cndmask_b32_e32 v92, v158, v92, vcc
	v_cmp_le_u32_e32 vcc, v131, v183
	v_add_u32_e32 v131, 21, v130
	s_nop 0
	v_cndmask_b32_e32 v76, v158, v76, vcc
	v_cmp_le_u32_e32 vcc, v131, v183
	v_add_u32_e32 v131, 53, v130
	s_nop 0
	v_cndmask_b32_e32 v93, v158, v93, vcc
	v_cmp_le_u32_e32 vcc, v131, v183
	v_add_u32_e32 v131, 22, v130
	s_nop 0
	v_cndmask_b32_e32 v77, v158, v77, vcc
	v_cmp_le_u32_e32 vcc, v131, v183
	v_add_u32_e32 v131, 54, v130
	s_nop 0
	v_cndmask_b32_e32 v94, v158, v94, vcc
	v_cmp_le_u32_e32 vcc, v131, v183
	v_add_u32_e32 v131, 23, v130
	v_add_u32_e32 v130, 55, v130
	v_cndmask_b32_e32 v78, v158, v78, vcc
	v_cmp_le_u32_e32 vcc, v131, v183
	s_nop 1
	v_cndmask_b32_e32 v95, v158, v95, vcc
	v_cmp_le_u32_e32 vcc, v130, v183
	s_nop 1
	v_cndmask_b32_e32 v79, v158, v79, vcc
.LBB0_283:
	v_max3_f32 v130, v80, v64, v81
	v_max3_f32 v131, v65, v82, v66
	s_cmp_lg_u32 s49, 0
	v_max3_f32 v130, v130, v83, v67
	v_max3_f32 v131, v131, v84, v68
	s_cselect_b64 s[72:73], -1, 0
	v_max3_f32 v130, v130, v85, v69
	v_max3_f32 v131, v131, v86, v70
	s_cmp_eq_u32 s49, 0
	v_max3_f32 v130, v130, v87, v71
	v_max3_f32 v131, v131, v88, v72
	s_nop 0
	v_max3_f32 v130, v130, v89, v73
	v_max3_f32 v131, v131, v90, v74
	s_nop 0
	v_max3_f32 v130, v130, v91, v75
	v_max3_f32 v131, v131, v92, v76
	s_nop 0
	v_max3_f32 v130, v130, v93, v77
	v_max3_f32 v131, v131, v94, v78
	s_nop 0
	v_max3_f32 v130, v130, v95, v79
	v_max_f32_e32 v131, v131, v131
	v_max_f32_e32 v130, v130, v130
	v_max_f32_e32 v130, v130, v131
	v_mov_b32_e32 v131, v130
	s_nop 1
	v_permlane32_swap_b32_e32 v130, v131
	v_max_f32_e32 v130, v130, v131
	s_cbranch_scc1 .LBB0_286
	s_mov_b32 s52, 0x42c00000
	v_cmp_lt_f32_e32 vcc, s52, v130
	s_cbranch_vccz .LBB0_287
	v_max_f32_e32 v130, v130, v130
	v_max_f32_e32 v130, 0, v130

.LBB0_288:
	s_andn2_b64 vcc, exec, s[72:73]
	s_cbranch_vccnz .LBB0_292
	v_exp_f32_e64 v131, -v130
	s_and_saveexec_b64 s[72:73], s[38:39]
	ds_write_b32 v173, v131
	s_or_b64 exec, exec, s[72:73]
	v_mul_f32_e32 v174, v174, v131
	s_waitcnt lgkmcnt(0)
	v_add_u32_e32 v131, s66, v172
	ds_read_b128 v[218:221], v131
	ds_read_b128 v[222:225], v131 offset:32
	ds_read_b128 v[226:229], v131 offset:64
	ds_read_b128 v[214:217], v131 offset:96
	s_waitcnt lgkmcnt(3)
	v_pk_mul_f32 v[50:51], v[50:51], v[220:221]
	s_waitcnt lgkmcnt(2)
	v_pk_mul_f32 v[52:53], v[52:53], v[222:223]
	s_waitcnt lgkmcnt(1)
	v_pk_mul_f32 v[56:57], v[56:57], v[226:227]
	s_waitcnt lgkmcnt(0)
	v_pk_mul_f32 v[60:61], v[60:61], v[214:215]
	v_pk_mul_f32 v[62:63], v[62:63], v[216:217]
	v_pk_mul_f32 v[58:59], v[58:59], v[228:229]
	v_pk_mul_f32 v[54:55], v[54:55], v[224:225]
	v_pk_mul_f32 v[48:49], v[48:49], v[218:219]
	v_pk_mul_f32 v[44:45], v[44:45], v[214:215]
	v_pk_mul_f32 v[40:41], v[40:41], v[226:227]
	v_pk_mul_f32 v[36:37], v[36:37], v[222:223]
	v_pk_mul_f32 v[46:47], v[46:47], v[216:217]
	v_pk_mul_f32 v[42:43], v[42:43], v[228:229]
	v_pk_mul_f32 v[38:39], v[38:39], v[224:225]
	v_pk_mul_f32 v[34:35], v[34:35], v[220:221]
	v_pk_mul_f32 v[32:33], v[32:33], v[218:219]
	v_pk_mul_f32 v[28:29], v[28:29], v[214:215]
	v_pk_mul_f32 v[24:25], v[24:25], v[226:227]
	v_pk_mul_f32 v[20:21], v[20:21], v[222:223]
	v_pk_mul_f32 v[30:31], v[30:31], v[216:217]
	v_pk_mul_f32 v[26:27], v[26:27], v[228:229]
	v_pk_mul_f32 v[22:23], v[22:23], v[224:225]
	v_pk_mul_f32 v[18:19], v[18:19], v[220:221]
	v_pk_mul_f32 v[16:17], v[16:17], v[218:219]
	v_pk_mul_f32 v[12:13], v[12:13], v[214:215]
	v_pk_mul_f32 v[8:9], v[8:9], v[226:227]
	v_pk_mul_f32 v[4:5], v[4:5], v[222:223]
	v_pk_mul_f32 v[14:15], v[14:15], v[216:217]
	v_pk_mul_f32 v[10:11], v[10:11], v[228:229]
	v_pk_mul_f32 v[6:7], v[6:7], v[224:225]
	v_pk_mul_f32 v[2:3], v[2:3], v[220:221]
	v_pk_mul_f32 v[0:1], v[0:1], v[218:219]

.LBB0_293:
	v_exp_f32_e32 v80, v80
	v_exp_f32_e32 v81, v81
	v_exp_f32_e32 v82, v82
	v_exp_f32_e32 v83, v83
	v_add_f32_e32 v185, 0, v80
	v_exp_f32_e32 v84, v84
	v_add_f32_e32 v185, v81, v185
	v_exp_f32_e32 v85, v85
	v_cvt_pk_bf16_f32 v80, v80, v81
	v_add_f32_e32 v81, v82, v185
	v_add_f32_e32 v185, v83, v81
	v_exp_f32_e32 v86, v86
	v_cvt_pk_bf16_f32 v81, v82, v83
	v_add_f32_e32 v82, v84, v185
	v_exp_f32_e32 v87, v87
	v_add_f32_e32 v83, v85, v82
	v_cvt_pk_bf16_f32 v82, v84, v85
	v_add_f32_e32 v83, v86, v83
	v_add_f32_e32 v84, v87, v83
	v_cvt_pk_bf16_f32 v83, v86, v87
	s_waitcnt lgkmcnt(7)
	s_nop 0
	v_mfma_f32_32x32x16_bf16 v[48:63], v[80:83], v[186:189], v[48:63]
	v_exp_f32_e32 v85, v88
	v_exp_f32_e32 v86, v89
	v_add_f32_e32 v84, v85, v84
	v_add_f32_e32 v87, v86, v84
	v_cvt_pk_bf16_f32 v84, v85, v86
	s_waitcnt lgkmcnt(5)
	v_mfma_f32_32x32x16_bf16 v[32:47], v[80:83], v[194:197], v[32:47]
	v_exp_f32_e32 v85, v90
	v_exp_f32_e32 v86, v91
	v_add_f32_e32 v87, v85, v87
	v_add_f32_e32 v87, v86, v87
	v_cvt_pk_bf16_f32 v85, v85, v86
	s_waitcnt lgkmcnt(3)
	v_mfma_f32_32x32x16_bf16 v[16:31], v[80:83], v[202:205], v[16:31]
	v_exp_f32_e32 v86, v92
	v_exp_f32_e32 v88, v93
	v_add_f32_e32 v87, v86, v87
	v_add_f32_e32 v87, v88, v87
	v_cvt_pk_bf16_f32 v86, v86, v88
	s_waitcnt lgkmcnt(1)
	v_mfma_f32_32x32x16_bf16 v[0:15], v[80:83], v[206:209], v[0:15]
	v_exp_f32_e32 v80, v94
	v_exp_f32_e32 v81, v95
	v_add_f32_e32 v82, v80, v87
	v_add_f32_e32 v185, v81, v82
	v_cvt_pk_bf16_f32 v87, v80, v81
	ds_read_b128 v[88:91], v139 offset:18496
	ds_read_b128 v[92:95], v139 offset:23104
	ds_read_b128 v[186:189], v139 offset:27712
	ds_read_b128 v[80:83], v139 offset:32320
	v_mfma_f32_32x32x16_bf16 v[48:63], v[84:87], v[190:193], v[48:63]
	v_exp_f32_e32 v64, v64
	v_exp_f32_e32 v65, v65
	v_add_f32_e32 v185, v64, v185
	v_add_f32_e32 v185, v65, v185
	v_cvt_pk_bf16_f32 v64, v64, v65
	v_mfma_f32_32x32x16_bf16 v[32:47], v[84:87], v[198:201], v[32:47]
	v_exp_f32_e32 v65, v66
	v_exp_f32_e32 v66, v67
	v_add_f32_e32 v67, v65, v185
	v_add_f32_e32 v67, v66, v67
	v_cvt_pk_bf16_f32 v65, v65, v66
	v_mfma_f32_32x32x16_bf16 v[16:31], v[84:87], v[134:137], v[16:31]
	v_exp_f32_e32 v66, v68
	v_exp_f32_e32 v68, v69
	v_add_f32_e32 v67, v66, v67
	v_add_f32_e32 v67, v68, v67
	v_cvt_pk_bf16_f32 v66, v66, v68
	s_waitcnt lgkmcnt(4)
	v_mfma_f32_32x32x16_bf16 v[0:15], v[84:87], v[210:213], v[0:15]
	v_exp_f32_e32 v68, v70
	v_exp_f32_e32 v69, v71
	v_add_f32_e32 v67, v68, v67
	v_add_f32_e32 v185, v69, v67
	v_cvt_pk_bf16_f32 v67, v68, v69
	ds_read_b128 v[68:71], v139 offset:18528
	ds_read_b128 v[84:87], v139 offset:23136
	ds_read_b128 v[130:133], v139 offset:27744
	ds_read_b128 v[134:137], v139 offset:32352
	s_waitcnt lgkmcnt(7)
	v_mfma_f32_32x32x16_bf16 v[48:63], v[64:67], v[88:91], v[48:63]
	v_exp_f32_e32 v72, v72
	v_exp_f32_e32 v73, v73
	v_add_f32_e32 v88, v72, v185
	v_add_f32_e32 v88, v73, v88
	v_cvt_pk_bf16_f32 v72, v72, v73
	s_waitcnt lgkmcnt(6)
	v_mfma_f32_32x32x16_bf16 v[32:47], v[64:67], v[92:95], v[32:47]
	v_exp_f32_e32 v73, v74
	v_exp_f32_e32 v74, v75
	v_add_f32_e32 v75, v73, v88
	v_add_f32_e32 v75, v74, v75
	v_cvt_pk_bf16_f32 v73, v73, v74
	s_waitcnt lgkmcnt(5)
	v_mfma_f32_32x32x16_bf16 v[16:31], v[64:67], v[186:189], v[16:31]
	v_exp_f32_e32 v74, v76
	v_exp_f32_e32 v76, v77
	v_add_f32_e32 v75, v74, v75
	v_add_f32_e32 v75, v76, v75
	v_cvt_pk_bf16_f32 v74, v74, v76
	s_waitcnt lgkmcnt(4)
	v_mfma_f32_32x32x16_bf16 v[0:15], v[64:67], v[80:83], v[0:15]
	v_exp_f32_e32 v64, v78
	v_exp_f32_e32 v65, v79
	v_add_f32_e32 v66, v64, v75
	v_add_f32_e32 v66, v65, v66
	v_cvt_pk_bf16_f32 v75, v64, v65
	s_waitcnt lgkmcnt(3)
	s_nop 0
	v_mfma_f32_32x32x16_bf16 v[48:63], v[72:75], v[68:71], v[48:63]
	s_waitcnt lgkmcnt(2)
	v_mfma_f32_32x32x16_bf16 v[32:47], v[72:75], v[84:87], v[32:47]
	s_waitcnt lgkmcnt(1)
	v_mfma_f32_32x32x16_bf16 v[16:31], v[72:75], v[130:133], v[16:31]
	s_waitcnt lgkmcnt(0)
	v_mfma_f32_32x32x16_bf16 v[0:15], v[72:75], v[134:137], v[0:15]
	v_add_f32_e32 v174, v174, v66
